# LayerNorm partial exchange via tag-in-data 16-byte write-through granules, readers re-read only missing owners; no store-ack wait, counter atomic or poll
# speedup vs baseline: 1.0209x; 1.0209x over previous
.LBB0_130:
	s_or_b64 exec, exec, s[40:41]
	s_movk_i32 s31, 0xffbf
	v_and_or_b32 v0, v109, s31, v111
	s_movk_i32 s31, 0x100
	v_cmp_gt_i32_e64 s[40:41], s31, v0
	v_ashrrev_i32_e32 v1, 31, v0
	s_waitcnt lgkmcnt(1)
	v_lshl_add_u32 v2, v0, 3, 0
	s_waitcnt lgkmcnt(0)
	s_barrier
	s_and_saveexec_b64 s[42:43], s[40:41]
	s_cbranch_execz .Lrz1_skip
	v_add_u32_e32 v3, 0x24000, v2
	s_lshl_b32 s31, s33, 3
	ds_read2st64_b64 v[4:7], v3 offset1:4
	s_add_i32 s30, s31, s30
	s_and_b32 s99, s30, 7
	s_ashr_i32 s31, s30, 31
	s_lshl_b64 s[30:31], s[30:31], 12
	s_add_u32 s30, s77, s30
	s_addc_u32 s31, s80, s31
	s_waitcnt lgkmcnt(0)
	v_add_f32_e32 v4, v4, v6
	v_add_f32_e32 v5, v5, v7
	v_lshl_add_u64 v[6:7], v[0:1], 4, s[30:31]
	v_mov_b32_e32 v176, v4
	v_mov_b32_e32 v177, 0x4c4e5447
	v_mov_b32_e32 v178, v5
	v_mov_b32_e32 v179, v177
	v_lshlrev_b32_e32 v212, 4, v0
	s_lshl_b32 s33, s33, 15
	s_add_u32 s50, s77, s33
	s_addc_u32 s51, s80, 0
	global_store_dwordx4 v[6:7], v[176:179], off sc1
	v_add_u32_e32 v213, 0x1000, v212
	v_add_u32_e32 v214, 0x2000, v212
	v_add_u32_e32 v215, 0x3000, v212
	v_add_u32_e32 v216, 0x4000, v212
	v_add_u32_e32 v217, 0x5000, v212
	v_add_u32_e32 v218, 0x6000, v212
	v_add_u32_e32 v219, 0x7000, v212
	v_add_u32_e32 v2, 0x24000, v2
	s_movk_i32 s98, 0xff
	s_cmp_lg_u32 s99, 0
	s_cbranch_scc1 .Lrz1_o0
	v_mov_b32_e32 v180, v4
	v_mov_b32_e32 v181, v177
	v_mov_b32_e32 v182, v5
	v_mov_b32_e32 v183, v177
	s_bitset0_b32 s98, 0
.Lrz1_o0:
	s_cmp_lg_u32 s99, 1
	s_cbranch_scc1 .Lrz1_o1
	v_mov_b32_e32 v184, v4
	v_mov_b32_e32 v185, v177
	v_mov_b32_e32 v186, v5
	v_mov_b32_e32 v187, v177
	s_bitset0_b32 s98, 1
.Lrz1_o1:
	s_cmp_lg_u32 s99, 2
	s_cbranch_scc1 .Lrz1_o2
	v_mov_b32_e32 v188, v4
	v_mov_b32_e32 v189, v177
	v_mov_b32_e32 v190, v5
	v_mov_b32_e32 v191, v177
	s_bitset0_b32 s98, 2
.Lrz1_o2:
	s_cmp_lg_u32 s99, 3
	s_cbranch_scc1 .Lrz1_o3
	v_mov_b32_e32 v192, v4
	v_mov_b32_e32 v193, v177
	v_mov_b32_e32 v194, v5
	v_mov_b32_e32 v195, v177
	s_bitset0_b32 s98, 3
.Lrz1_o3:
	s_cmp_lg_u32 s99, 4
	s_cbranch_scc1 .Lrz1_o4
	v_mov_b32_e32 v196, v4
	v_mov_b32_e32 v197, v177
	v_mov_b32_e32 v198, v5
	v_mov_b32_e32 v199, v177
	s_bitset0_b32 s98, 4
.Lrz1_o4:
	s_cmp_lg_u32 s99, 5
	s_cbranch_scc1 .Lrz1_o5
	v_mov_b32_e32 v200, v4
	v_mov_b32_e32 v201, v177
	v_mov_b32_e32 v202, v5
	v_mov_b32_e32 v203, v177
	s_bitset0_b32 s98, 5
.Lrz1_o5:
	s_cmp_lg_u32 s99, 6
	s_cbranch_scc1 .Lrz1_o6
	v_mov_b32_e32 v204, v4
	v_mov_b32_e32 v205, v177
	v_mov_b32_e32 v206, v5
	v_mov_b32_e32 v207, v177
	s_bitset0_b32 s98, 6
.Lrz1_o6:
	s_cmp_lg_u32 s99, 7
	s_cbranch_scc1 .Lrz1_o7
	v_mov_b32_e32 v208, v4
	v_mov_b32_e32 v209, v177
	v_mov_b32_e32 v210, v5
	v_mov_b32_e32 v211, v177
	s_bitset0_b32 s98, 7
.Lrz1_o7:
	s_mov_b32 s99, 0
.Lrz1_pass:
	s_bitcmp0_b32 s98, 0
	s_cbranch_scc1 .Lrz1_l0
	global_load_dwordx4 v[180:183], v212, s[50:51] sc1
.Lrz1_l0:
	s_bitcmp0_b32 s98, 1
	s_cbranch_scc1 .Lrz1_l1
	global_load_dwordx4 v[184:187], v213, s[50:51] sc1
.Lrz1_l1:
	s_bitcmp0_b32 s98, 2
	s_cbranch_scc1 .Lrz1_l2
	global_load_dwordx4 v[188:191], v214, s[50:51] sc1
.Lrz1_l2:
	s_bitcmp0_b32 s98, 3
	s_cbranch_scc1 .Lrz1_l3
	global_load_dwordx4 v[192:195], v215, s[50:51] sc1
.Lrz1_l3:
	s_bitcmp0_b32 s98, 4
	s_cbranch_scc1 .Lrz1_l4
	global_load_dwordx4 v[196:199], v216, s[50:51] sc1
.Lrz1_l4:
	s_bitcmp0_b32 s98, 5
	s_cbranch_scc1 .Lrz1_l5
	global_load_dwordx4 v[200:203], v217, s[50:51] sc1
.Lrz1_l5:
	s_bitcmp0_b32 s98, 6
	s_cbranch_scc1 .Lrz1_l6
	global_load_dwordx4 v[204:207], v218, s[50:51] sc1
.Lrz1_l6:
	s_bitcmp0_b32 s98, 7
	s_cbranch_scc1 .Lrz1_l7
	global_load_dwordx4 v[208:211], v219, s[50:51] sc1
.Lrz1_l7:
	s_waitcnt vmcnt(0)
	v_xor_b32_e32 v220, v177, v181
	v_xor_b32_e32 v221, v177, v183
	v_or_b32_e32 v220, v220, v221
	v_cmp_eq_u32_e32 vcc, 0, v220
	s_nop 1
	s_cmp_eq_u64 vcc, exec
	s_cbranch_scc0 .Lrz1_c0
	s_bitset0_b32 s98, 0
.Lrz1_c0:
	v_xor_b32_e32 v220, v177, v185
	v_xor_b32_e32 v221, v177, v187
	v_or_b32_e32 v220, v220, v221
	v_cmp_eq_u32_e32 vcc, 0, v220
	s_nop 1
	s_cmp_eq_u64 vcc, exec
	s_cbranch_scc0 .Lrz1_c1
	s_bitset0_b32 s98, 1
.Lrz1_c1:
	v_xor_b32_e32 v220, v177, v189
	v_xor_b32_e32 v221, v177, v191
	v_or_b32_e32 v220, v220, v221
	v_cmp_eq_u32_e32 vcc, 0, v220
	s_nop 1
	s_cmp_eq_u64 vcc, exec
	s_cbranch_scc0 .Lrz1_c2
	s_bitset0_b32 s98, 2
.Lrz1_c2:
	v_xor_b32_e32 v220, v177, v193
	v_xor_b32_e32 v221, v177, v195
	v_or_b32_e32 v220, v220, v221
	v_cmp_eq_u32_e32 vcc, 0, v220
	s_nop 1
	s_cmp_eq_u64 vcc, exec
	s_cbranch_scc0 .Lrz1_c3
	s_bitset0_b32 s98, 3
.Lrz1_c3:
	v_xor_b32_e32 v220, v177, v197
	v_xor_b32_e32 v221, v177, v199
	v_or_b32_e32 v220, v220, v221
	v_cmp_eq_u32_e32 vcc, 0, v220
	s_nop 1
	s_cmp_eq_u64 vcc, exec
	s_cbranch_scc0 .Lrz1_c4
	s_bitset0_b32 s98, 4
.Lrz1_c4:
	v_xor_b32_e32 v220, v177, v201
	v_xor_b32_e32 v221, v177, v203
	v_or_b32_e32 v220, v220, v221
	v_cmp_eq_u32_e32 vcc, 0, v220
	s_nop 1
	s_cmp_eq_u64 vcc, exec
	s_cbranch_scc0 .Lrz1_c5
	s_bitset0_b32 s98, 5
.Lrz1_c5:
	v_xor_b32_e32 v220, v177, v205
	v_xor_b32_e32 v221, v177, v207
	v_or_b32_e32 v220, v220, v221
	v_cmp_eq_u32_e32 vcc, 0, v220
	s_nop 1
	s_cmp_eq_u64 vcc, exec
	s_cbranch_scc0 .Lrz1_c6
	s_bitset0_b32 s98, 6
.Lrz1_c6:
	v_xor_b32_e32 v220, v177, v209
	v_xor_b32_e32 v221, v177, v211
	v_or_b32_e32 v220, v220, v221
	v_cmp_eq_u32_e32 vcc, 0, v220
	s_nop 1
	s_cmp_eq_u64 vcc, exec
	s_cbranch_scc0 .Lrz1_c7
	s_bitset0_b32 s98, 7
.Lrz1_c7:
	s_cmp_eq_u32 s98, 0
	s_cbranch_scc1 .Lrz1_done
	s_sleep 4
	s_add_i32 s99, s99, 1
	s_cmp_lt_u32 s99, 0x1000
	s_cbranch_scc1 .Lrz1_pass
.Lrz1_done:
	v_add_f32_e32 v3, 0, v180
	v_add_f32_e32 v6, 0, v182
	v_add_f32_e32 v3, v3, v184
	v_add_f32_e32 v6, v6, v186
	v_add_f32_e32 v3, v3, v188
	v_add_f32_e32 v6, v6, v190
	v_add_f32_e32 v3, v3, v192
	v_add_f32_e32 v6, v6, v194
	v_add_f32_e32 v3, v3, v196
	v_add_f32_e32 v6, v6, v198
	v_add_f32_e32 v3, v3, v200
	v_add_f32_e32 v6, v6, v202
	v_add_f32_e32 v3, v3, v204
	v_add_f32_e32 v6, v6, v206
	v_add_f32_e32 v3, v3, v208
	v_add_f32_e32 v6, v6, v210
	v_mov_b32_e32 v1, v6
	s_mov_b32 s33, 0x3a800000
	v_mul_f32_e32 v0, 0x3a800000, v3
	v_mul_f32_e32 v3, v0, v0
	v_fma_f32 v1, v1, s33, -v3
	v_max_f32_e32 v1, 0, v1
	v_add_f32_e32 v1, 0x358637bd, v1
	s_mov_b32 s33, 0xf800000
	v_mul_f32_e32 v3, 0x4f800000, v1
	v_cmp_gt_f32_e32 vcc, s33, v1
	s_nop 1
	v_cndmask_b32_e32 v1, v1, v3, vcc
	v_sqrt_f32_e32 v3, v1
	s_nop 0
	v_add_u32_e32 v4, -1, v3
	v_add_u32_e32 v5, 1, v3
	v_fma_f32 v6, -v4, v3, v1
	v_fma_f32 v7, -v5, v3, v1
	v_cmp_ge_f32_e64 s[40:41], 0, v6
	s_nop 1
	v_cndmask_b32_e64 v3, v3, v4, s[40:41]
	v_cmp_lt_f32_e64 s[40:41], 0, v7
	s_nop 1
	v_cndmask_b32_e64 v3, v3, v5, s[40:41]
	v_mul_f32_e32 v4, 0x37800000, v3
	v_cndmask_b32_e32 v3, v3, v4, vcc
	v_cmp_class_f32_e32 vcc, v1, v157
	s_nop 1
	v_cndmask_b32_e32 v1, v3, v1, vcc
	v_div_scale_f32 v3, s[40:41], v1, v1, 1.0
	v_rcp_f32_e32 v4, v3
	v_div_scale_f32 v5, vcc, 1.0, v1, 1.0
	v_fma_f32 v6, -v3, v4, 1.0
	v_fmac_f32_e32 v4, v6, v4
	v_mul_f32_e32 v6, v5, v4
	v_fma_f32 v7, -v3, v6, v5
	v_fmac_f32_e32 v6, v7, v4
	v_fma_f32 v3, -v3, v6, v5
	v_div_fmas_f32 v3, v3, v4, v6
	v_div_fixup_f32 v1, v3, v1, 1.0
	ds_write_b64 v2, v[0:1]
.Lrz1_skip:
	s_mov_b64 s[30:31], s[42:43]
	s_branch .LBB0_39

.LBB0_726:
	s_or_b64 exec, exec, s[40:41]
	s_movk_i32 s40, 0xffbf
	v_and_or_b32 v0, v102, s40, v103
	s_movk_i32 s40, 0x100
	v_cmp_gt_i32_e64 s[40:41], s40, v0
	v_ashrrev_i32_e32 v1, 31, v0
	s_waitcnt lgkmcnt(1)
	v_lshl_add_u32 v2, v0, 3, 0
	s_waitcnt lgkmcnt(0)
	s_barrier
	s_and_saveexec_b64 s[44:45], s[40:41]
	s_cbranch_execz .LBB0_747
	v_add_u32_e32 v3, 0x24000, v2
	s_lshl_b32 s47, s33, 3
	ds_read2st64_b64 v[4:7], v3 offset1:4
	s_add_i32 s46, s47, s46
	s_and_b32 s99, s46, 7
	s_ashr_i32 s47, s46, 31
	s_lshl_b64 s[46:47], s[46:47], 12
	s_add_u32 s46, s81, s46
	s_addc_u32 s47, s84, s47
	s_waitcnt lgkmcnt(0)
	v_add_f32_e32 v4, v4, v6
	v_add_f32_e32 v5, v5, v7
	v_lshl_add_u64 v[6:7], v[0:1], 4, s[46:47]
	v_mov_b32_e32 v176, v4
	v_mov_b32_e32 v177, 0x4c4e5447
	v_mov_b32_e32 v178, v5
	v_mov_b32_e32 v179, v177
	v_lshlrev_b32_e32 v212, 4, v0
	s_lshl_b32 s33, s33, 15
	s_add_u32 s50, s81, s33
	s_addc_u32 s51, s84, 0
	global_store_dwordx4 v[6:7], v[176:179], off sc1
	v_add_u32_e32 v213, 0x1000, v212
	v_add_u32_e32 v214, 0x2000, v212
	v_add_u32_e32 v215, 0x3000, v212
	v_add_u32_e32 v216, 0x4000, v212
	v_add_u32_e32 v217, 0x5000, v212
	v_add_u32_e32 v218, 0x6000, v212
	v_add_u32_e32 v219, 0x7000, v212
	v_add_u32_e32 v2, 0x24000, v2
	s_movk_i32 s98, 0xff
	s_cmp_lg_u32 s99, 0
	s_cbranch_scc1 .Lrz2_o0
	v_mov_b32_e32 v180, v4
	v_mov_b32_e32 v181, v177
	v_mov_b32_e32 v182, v5
	v_mov_b32_e32 v183, v177
	s_bitset0_b32 s98, 0

.LBB0_1078:
	s_and_b64 vcc, exec, s[0:1]
	s_cbranch_vccz .LBB0_1144
	s_waitcnt lgkmcnt(0)
	v_readlane_b32 s98, v254, 0
	s_lshl_b32 s99, s98, 15
	s_add_u32 s99, s99, 0x158a0000
	s_add_u32 s98, s48, s99
	s_addc_u32 s99, s49, 0
	v_lshlrev_b32_e32 v176, 4, v156
	v_add_u32_e32 v177, 0x2000, v176
	v_add_u32_e32 v178, 0x4000, v176
	v_add_u32_e32 v179, 0x6000, v176
	v_mov_b32_e32 v180, 0
	v_mov_b32_e32 v181, 0
	v_mov_b32_e32 v182, 0
	v_mov_b32_e32 v183, 0
	global_store_dwordx4 v176, v[180:183], s[98:99] sc1
	global_store_dwordx4 v177, v[180:183], s[98:99] sc1
	global_store_dwordx4 v178, v[180:183], s[98:99] sc1
	global_store_dwordx4 v179, v[180:183], s[98:99] sc1
	s_add_u32 s76, s48, 0x8c04000
	s_addc_u32 s77, s49, 0
	s_add_u32 s93, s48, 0x5c04000
	s_addc_u32 s0, s49, 0
	v_writelane_b32 v255, s0, 0
	s_add_u32 s0, s48, 0x7c04000
	v_writelane_b32 v255, s0, 2
	s_addc_u32 s0, s49, 0
	s_add_u32 s46, s48, 0x8c24000
	s_addc_u32 s47, s49, 0
	s_add_u32 s50, s48, 0x3a04
	s_addc_u32 s51, s49, 0
	v_writelane_b32 v255, s0, 4
	s_add_u32 s0, s72, 0xd8
	s_addc_u32 s1, s73, 0
	v_writelane_b32 v255, s0, 6
	s_mov_b64 s[4:5], s[80:81]
	v_mov_b32_e32 v46, v156
	v_writelane_b32 v255, s1, 7
	s_add_u32 s0, s72, 0xd0
	s_addc_u32 s1, s73, 0
	v_writelane_b32 v255, s0, 8
	s_nop 1
	v_writelane_b32 v255, s1, 9
	s_add_u32 s0, s72, 0xa8
	s_addc_u32 s1, s73, 0
	v_writelane_b32 v255, s0, 10
	s_nop 1
	v_writelane_b32 v255, s1, 11
	s_add_u32 s0, s72, 0xa0
	s_addc_u32 s1, s73, 0
	v_writelane_b32 v255, s0, 12
	s_nop 1
	v_writelane_b32 v255, s1, 13
	s_add_u32 s0, s72, 0x58
	s_addc_u32 s1, s73, 0
	v_writelane_b32 v255, s0, 14
	s_nop 1
	v_writelane_b32 v255, s1, 15
	v_readlane_b32 s0, v254, 0
	s_mov_b32 s80, s0
	s_load_dword s92, s[4:5], 0x0
	s_cmpk_lt_i32 s80, 0x80
	s_cselect_b64 s[0:1], -1, 0
	s_cmpk_gt_i32 s80, 0x7f
	s_cselect_b64 s[4:5], -1, 0
	v_writelane_b32 v255, s4, 16
	s_waitcnt lgkmcnt(0)
	s_cmpk_eq_i32 s92, 0x100
	v_writelane_b32 v255, s5, 17
	s_mov_b64 s[4:5], -1
	s_cbranch_scc1 .LBB0_1328
	s_andn2_b64 vcc, exec, s[0:1]
	s_cbranch_vccnz .LBB0_1145
	s_mov_b32 s33, s80
	s_mov_b32 s0, s80
	s_branch .LBB0_1083
